# RG-LRU pass 3 backward final scan: 16 serialized GY load/wait/store steps -> 16 loads up front, LDS reads a group ahead, stores in flight
# speedup vs baseline: 1.0347x; 1.0119x over previous
.LBB0_295:
	s_or_b64 exec, exec, s[2:3]
	s_mov_b64 s[8:9], s[74:75]
	s_or_b32 s2, s35, s36
	s_lshl_b32 s3, s26, 1
	s_add_u32 s8, s8, s3
	s_addc_u32 s9, s9, 0
	v_lshlrev_b32_e32 v144, 1, v8
	v_add_u32_e32 v48, s2, v141
	v_lshl_add_u64 v[8:9], s[8:9], 0, v[144:145]
	s_mov_b64 s[8:9], 0xa1e0000
	v_ashrrev_i32_e32 v49, 31, v48
	v_lshl_add_u64 v[8:9], v[8:9], 0, s[8:9]
	v_lshlrev_b64 v[48:49], 10, v[48:49]
	s_mov_b64 s[98:99], 0x1000
	v_lshl_add_u64 v[48:49], v[8:9], 0, v[48:49]
	v_lshl_add_u64 v[52:53], v[48:49], 0, s[98:99]
	s_mov_b64 s[98:99], 0x3000
	v_lshl_add_u64 v[54:55], v[48:49], 0, s[98:99]
	global_load_ushort v216, v[54:55], off offset:3072
	global_load_ushort v217, v[54:55], off offset:2048
	global_load_ushort v218, v[54:55], off offset:1024
	global_load_ushort v219, v[54:55], off
	global_load_ushort v220, v[54:55], off offset:-1024
	global_load_ushort v221, v[54:55], off offset:-2048
	global_load_ushort v222, v[54:55], off offset:-3072
	global_load_ushort v223, v[54:55], off offset:-4096
	global_load_ushort v224, v[52:53], off offset:3072
	global_load_ushort v225, v[52:53], off offset:2048
	global_load_ushort v226, v[52:53], off offset:1024
	global_load_ushort v227, v[52:53], off
	global_load_ushort v228, v[52:53], off offset:-1024
	global_load_ushort v229, v[52:53], off offset:-2048
	global_load_ushort v230, v[52:53], off offset:-3072
	global_load_ushort v231, v[52:53], off offset:-4096
	v_lshl_or_b32 v50, v141, 8, v10
	v_add_u32_e32 v50, s60, v50
	s_add_i32 s28, s28, 1
	s_add_i32 s34, s34, s70
	s_cmp_eq_u32 s28, s0
	ds_read2st64_b32 v[56:57], v50 offset0:47 offset1:111
	ds_read_b32 v64, v50 offset:48896
	ds_read2st64_b32 v[58:59], v50 offset0:46 offset1:110
	ds_read_b32 v65, v50 offset:48640
	ds_read2st64_b32 v[60:61], v50 offset0:45 offset1:109
	ds_read_b32 v66, v50 offset:48384
	ds_read2st64_b32 v[62:63], v50 offset0:44 offset1:108
	ds_read_b32 v67, v50 offset:48128
	ds_read2st64_b32 v[162:163], v50 offset0:43 offset1:107
	ds_read_b32 v170, v50 offset:47872
	ds_read2st64_b32 v[164:165], v50 offset0:42 offset1:106
	ds_read_b32 v171, v50 offset:47616
	ds_read2st64_b32 v[166:167], v50 offset0:41 offset1:105
	ds_read_b32 v172, v50 offset:47360
	ds_read2st64_b32 v[168:169], v50 offset0:40 offset1:104
	ds_read_b32 v173, v50 offset:47104
	s_waitcnt lgkmcnt(14)
	v_fmac_f32_e32 v57, v11, v56
	v_add_f32_e32 v68, v64, v57
	s_waitcnt vmcnt(15)
	v_lshlrev_b32_e32 v69, 16, v216
	v_mul_f32_e32 v68, v68, v69
	v_bfe_u32 v69, v68, 16, 1
	v_add3_u32 v68, v68, v69, s83
	global_store_short_d16_hi v[54:55], v68, off offset:3072
	s_waitcnt lgkmcnt(12)
	v_fmac_f32_e32 v59, v57, v58
	v_add_f32_e32 v68, v65, v59
	s_waitcnt vmcnt(15)
	v_lshlrev_b32_e32 v69, 16, v217
	v_mul_f32_e32 v68, v68, v69
	v_bfe_u32 v69, v68, 16, 1
	v_add3_u32 v68, v68, v69, s83
	global_store_short_d16_hi v[54:55], v68, off offset:2048
	s_waitcnt lgkmcnt(10)
	v_fmac_f32_e32 v61, v59, v60
	v_add_f32_e32 v68, v66, v61
	s_waitcnt vmcnt(15)
	v_lshlrev_b32_e32 v69, 16, v218
	v_mul_f32_e32 v68, v68, v69
	v_bfe_u32 v69, v68, 16, 1
	v_add3_u32 v68, v68, v69, s83
	global_store_short_d16_hi v[54:55], v68, off offset:1024
	s_waitcnt lgkmcnt(8)
	v_fmac_f32_e32 v63, v61, v62
	v_add_f32_e32 v68, v67, v63
	s_waitcnt vmcnt(15)
	v_lshlrev_b32_e32 v69, 16, v219
	v_mul_f32_e32 v68, v68, v69
	v_bfe_u32 v69, v68, 16, 1
	v_add3_u32 v68, v68, v69, s83
	global_store_short_d16_hi v[54:55], v68, off
	v_mov_b32_e32 v11, v63
	ds_read2st64_b32 v[56:57], v50 offset0:39 offset1:103
	ds_read_b32 v64, v50 offset:46848
	ds_read2st64_b32 v[58:59], v50 offset0:38 offset1:102
	ds_read_b32 v65, v50 offset:46592
	ds_read2st64_b32 v[60:61], v50 offset0:37 offset1:101
	ds_read_b32 v66, v50 offset:46336
	ds_read2st64_b32 v[62:63], v50 offset0:36 offset1:100
	ds_read_b32 v67, v50 offset:46080
	s_waitcnt lgkmcnt(14)
	v_fmac_f32_e32 v163, v11, v162
	v_add_f32_e32 v68, v170, v163
	s_waitcnt vmcnt(15)
	v_lshlrev_b32_e32 v69, 16, v220
	v_mul_f32_e32 v68, v68, v69
	v_bfe_u32 v69, v68, 16, 1
	v_add3_u32 v68, v68, v69, s83
	global_store_short_d16_hi v[54:55], v68, off offset:-1024
	s_waitcnt lgkmcnt(12)
	v_fmac_f32_e32 v165, v163, v164
	v_add_f32_e32 v68, v171, v165
	s_waitcnt vmcnt(15)
	v_lshlrev_b32_e32 v69, 16, v221
	v_mul_f32_e32 v68, v68, v69
	v_bfe_u32 v69, v68, 16, 1
	v_add3_u32 v68, v68, v69, s83
	global_store_short_d16_hi v[54:55], v68, off offset:-2048
	s_waitcnt lgkmcnt(10)
	v_fmac_f32_e32 v167, v165, v166
	v_add_f32_e32 v68, v172, v167
	s_waitcnt vmcnt(15)
	v_lshlrev_b32_e32 v69, 16, v222
	v_mul_f32_e32 v68, v68, v69
	v_bfe_u32 v69, v68, 16, 1
	v_add3_u32 v68, v68, v69, s83
	global_store_short_d16_hi v[54:55], v68, off offset:-3072
	s_waitcnt lgkmcnt(8)
	v_fmac_f32_e32 v169, v167, v168
	v_add_f32_e32 v68, v173, v169
	s_waitcnt vmcnt(15)
	v_lshlrev_b32_e32 v69, 16, v223
	v_mul_f32_e32 v68, v68, v69
	v_bfe_u32 v69, v68, 16, 1
	v_add3_u32 v68, v68, v69, s83
	global_store_short_d16_hi v[54:55], v68, off offset:-4096
	v_mov_b32_e32 v11, v169
	ds_read2st64_b32 v[162:163], v50 offset0:35 offset1:99
	ds_read_b32 v170, v50 offset:45824
	ds_read2st64_b32 v[164:165], v50 offset0:34 offset1:98
	ds_read_b32 v171, v50 offset:45568
	ds_read2st64_b32 v[166:167], v50 offset0:33 offset1:97
	ds_read_b32 v172, v50 offset:45312
	ds_read2st64_b32 v[168:169], v50 offset0:32 offset1:96
	ds_read_b32 v173, v50 offset:45056
	s_waitcnt lgkmcnt(14)
	v_fmac_f32_e32 v57, v11, v56
	v_add_f32_e32 v68, v64, v57
	s_waitcnt vmcnt(15)
	v_lshlrev_b32_e32 v69, 16, v224
	v_mul_f32_e32 v68, v68, v69
	v_bfe_u32 v69, v68, 16, 1
	v_add3_u32 v68, v68, v69, s83
	global_store_short_d16_hi v[52:53], v68, off offset:3072
	s_waitcnt lgkmcnt(12)
	v_fmac_f32_e32 v59, v57, v58
	v_add_f32_e32 v68, v65, v59
	s_waitcnt vmcnt(15)
	v_lshlrev_b32_e32 v69, 16, v225
	v_mul_f32_e32 v68, v68, v69
	v_bfe_u32 v69, v68, 16, 1
	v_add3_u32 v68, v68, v69, s83
	global_store_short_d16_hi v[52:53], v68, off offset:2048
	s_waitcnt lgkmcnt(10)
	v_fmac_f32_e32 v61, v59, v60
	v_add_f32_e32 v68, v66, v61
	s_waitcnt vmcnt(15)
	v_lshlrev_b32_e32 v69, 16, v226
	v_mul_f32_e32 v68, v68, v69
	v_bfe_u32 v69, v68, 16, 1
	v_add3_u32 v68, v68, v69, s83
	global_store_short_d16_hi v[52:53], v68, off offset:1024
	s_waitcnt lgkmcnt(8)
	v_fmac_f32_e32 v63, v61, v62
	v_add_f32_e32 v68, v67, v63
	s_waitcnt vmcnt(15)
	v_lshlrev_b32_e32 v69, 16, v227
	v_mul_f32_e32 v68, v68, v69
	v_bfe_u32 v69, v68, 16, 1
	v_add3_u32 v68, v68, v69, s83
	global_store_short_d16_hi v[52:53], v68, off
	v_mov_b32_e32 v11, v63
	s_waitcnt lgkmcnt(6)
	v_fmac_f32_e32 v163, v11, v162
	v_add_f32_e32 v68, v170, v163
	s_waitcnt vmcnt(15)
	v_lshlrev_b32_e32 v69, 16, v228
	v_mul_f32_e32 v68, v68, v69
	v_bfe_u32 v69, v68, 16, 1
	v_add3_u32 v68, v68, v69, s83
	global_store_short_d16_hi v[52:53], v68, off offset:-1024
	s_waitcnt lgkmcnt(4)
	v_fmac_f32_e32 v165, v163, v164
	v_add_f32_e32 v68, v171, v165
	s_waitcnt vmcnt(15)
	v_lshlrev_b32_e32 v69, 16, v229
	v_mul_f32_e32 v68, v68, v69
	v_bfe_u32 v69, v68, 16, 1
	v_add3_u32 v68, v68, v69, s83
	global_store_short_d16_hi v[52:53], v68, off offset:-2048
	s_waitcnt lgkmcnt(2)
	v_fmac_f32_e32 v167, v165, v166
	v_add_f32_e32 v68, v172, v167
	s_waitcnt vmcnt(15)
	v_lshlrev_b32_e32 v69, 16, v230
	v_mul_f32_e32 v68, v68, v69
	v_bfe_u32 v69, v68, 16, 1
	v_add3_u32 v68, v68, v69, s83
	global_store_short_d16_hi v[52:53], v68, off offset:-3072
	s_waitcnt lgkmcnt(0)
	v_fmac_f32_e32 v169, v167, v168
	v_add_f32_e32 v68, v173, v169
	s_waitcnt vmcnt(15)
	v_lshlrev_b32_e32 v69, 16, v231
	v_mul_f32_e32 v68, v68, v69
	v_bfe_u32 v69, v68, 16, 1
	v_add3_u32 v68, v68, v69, s83
	global_store_short_d16_hi v[52:53], v68, off offset:-4096
	s_waitcnt lgkmcnt(0)
	s_barrier
	s_cbranch_scc1 .LBB0_371
